# stack4: + attention threshold test on per-half row max (cross-half combine only on the rare new-max path)
# baseline (speedup 1.0000x reference)
; __device__ __forceinline__ s16x4 vtr(lds_cptr p) { return __builtin_bit_cast(s16x4, __builtin_amdgcn_ds_read_tr16_b64_v4i16((LAS v4i16_t*)p)); }
; template <bool FIRST> __device__ __forceinline__ void partialSM(f32x16& p0, f32x16& p1, float& mref, f32x16& negm, float& alpha) {
;   constexpr float THRL = THR * 1.4426950408889634f;
;   float pmax = p0[0];
; #pragma unroll
;   for (int r = 1; r < 16; ++r) pmax = fmaxf(pmax, p0[r]);
; #pragma unroll
;   for (int r = 0; r < 16; ++r) pmax = fmaxf(pmax, p1[r]);
;   { auto rr = __builtin_amdgcn_permlane32_swap(__float_as_uint(pmax), __float_as_uint(pmax), false, false);
;     pmax = fmaxf(__uint_as_float(rr[0]), __uint_as_float(rr[1])); }
;   if (!FIRST && __builtin_expect(__all(pmax <= THRL), 1)) { alpha = 1.f; }
; template <int D0> __device__ __forceinline__ void pv_one(f32x16& od, lds_cptr vp, bf16x8 pa0, bf16x8 pa1, bf16x8 pa2, bf16x8 pa3) {
;   const s16x4 l0 = vtr(vp + v_rd_off(D0, 0, 0)), h0 = vtr(vp + v_rd_off(D0, 0, 1)), l1 = vtr(vp + v_rd_off(D0, 1, 0)), h1 = vtr(vp + v_rd_off(D0, 1, 1));
;   const s16x4 l2 = vtr(vp + v_rd_off(D0, 2, 0)), h2 = vtr(vp + v_rd_off(D0, 2, 1)), l3 = vtr(vp + v_rd_off(D0, 3, 0)), h3 = vtr(vp + v_rd_off(D0, 3, 1));
;     ...
;   od = __builtin_amdgcn_mfma_f32_32x32x16_bf16(pa0, PK(l0, h0), od, 0, 0, 0);
;   od = __builtin_amdgcn_mfma_f32_32x32x16_bf16(pa1, PK(l1, h1), od, 0, 0, 0);
;   od = __builtin_amdgcn_mfma_f32_32x32x16_bf16(pa2, PK(l2, h2), od, 0, 0, 0);
;   od = __builtin_amdgcn_mfma_f32_32x32x16_bf16(pa3, PK(l3, h3), od, 0, 0, 0);
;     ...
; }
; __device__ __forceinline__ void pv_d0(f32x16* o, lds_cptr vp, bf16x8 pa0, bf16x8 pa1, bf16x8 pa2, bf16x8 pa3) {
;   pv_one<0>(o[0], vp, pa0, pa1, pa2, pa3); pv_one<1>(o[1], vp, pa0, pa1, pa2, pa3);
.Lf1_741:
	s_and_b32 s48, s89, 0xc000
	ds_read_b64_tr_b16 v[64:65], v203
	ds_read_b64_tr_b16 v[66:67], v203 offset:2048
	ds_read_b64_tr_b16 v[70:71], v203 offset:2560
	ds_read_b64_tr_b16 v[68:69], v203 offset:512
	s_waitcnt lgkmcnt(2)
	v_mfma_f32_32x32x16_bf16 v[0:15], v[60:63], v[64:67], v[0:15]
	ds_read_b64_tr_b16 v[64:65], v203 offset:4096
	ds_read_b64_tr_b16 v[66:67], v203 offset:6144
	ds_read_b64_tr_b16 v[74:75], v203 offset:6656
	ds_read_b64_tr_b16 v[72:73], v203 offset:4608
	s_waitcnt lgkmcnt(2)
	v_mfma_f32_32x32x16_bf16 v[0:15], v[56:59], v[64:67], v[0:15]
	ds_read_b64_tr_b16 v[64:65], v203 offset:8192
	ds_read_b64_tr_b16 v[66:67], v203 offset:10240
	ds_read_b64_tr_b16 v[78:79], v203 offset:10752
	ds_read_b64_tr_b16 v[76:77], v203 offset:8704
	v_mfma_f32_32x32x16_bf16 v[16:31], v[60:63], v[68:71], v[16:31]
	s_waitcnt lgkmcnt(2)
	v_mfma_f32_32x32x16_bf16 v[0:15], v[52:55], v[64:67], v[0:15]
	ds_read_b64_tr_b16 v[64:65], v203 offset:12288
	ds_read_b64_tr_b16 v[66:67], v203 offset:14336
	ds_read_b64_tr_b16 v[186:187], v203 offset:14848
	ds_read_b64_tr_b16 v[184:185], v203 offset:12800
	v_mfma_f32_32x32x16_bf16 v[16:31], v[56:59], v[72:75], v[16:31]
	s_waitcnt lgkmcnt(2)
	v_mfma_f32_32x32x16_bf16 v[0:15], v[48:51], v[64:67], v[0:15]
	v_max_f32_e32 v64, v96, v97
	v_max3_f32 v64, v64, v98, v99
	v_max3_f32 v60, v64, v100, v101
	v_max3_f32 v60, v60, v102, v103
	v_max3_f32 v60, v60, v104, v105
	v_max3_f32 v60, v60, v106, v107
	v_max3_f32 v60, v60, v108, v109
	v_mfma_f32_32x32x16_bf16 v[16:31], v[52:55], v[76:79], v[16:31]
	v_max3_f32 v60, v60, v110, v111
	v_max3_f32 v60, v60, v80, v81
	v_max3_f32 v56, v60, v82, v83
	v_max3_f32 v56, v56, v84, v85
	v_max3_f32 v56, v56, v86, v87
	v_max3_f32 v56, v56, v88, v89
	v_max3_f32 v56, v56, v90, v91
	v_max3_f32 v56, v56, v92, v93
	s_waitcnt lgkmcnt(0)
	v_mfma_f32_32x32x16_bf16 v[16:31], v[48:51], v[184:187], v[16:31]
	v_max3_f32 v56, v56, v94, v95
	v_cmp_ge_f32_e32 vcc, s86, v56
	s_cmp_eq_u64 vcc, exec
	s_cbranch_scc0 .Lf1_757
	v_mov_b32_e32 v169, 1.0

; __device__ __forceinline__ s16x4 vtr(lds_cptr p) { return __builtin_bit_cast(s16x4, __builtin_amdgcn_ds_read_tr16_b64_v4i16((LAS v4i16_t*)p)); }
; template <bool FIRST> __device__ __forceinline__ void partialSM(f32x16& p0, f32x16& p1, float& mref, f32x16& negm, float& alpha) {
;   constexpr float THRL = THR * 1.4426950408889634f;
;   float pmax = p0[0];
; #pragma unroll
;   for (int r = 1; r < 16; ++r) pmax = fmaxf(pmax, p0[r]);
; #pragma unroll
;   for (int r = 0; r < 16; ++r) pmax = fmaxf(pmax, p1[r]);
;   { auto rr = __builtin_amdgcn_permlane32_swap(__float_as_uint(pmax), __float_as_uint(pmax), false, false);
;     pmax = fmaxf(__uint_as_float(rr[0]), __uint_as_float(rr[1])); }
;   if (!FIRST && __builtin_expect(__all(pmax <= THRL), 1)) { alpha = 1.f; }
; template <int D0> __device__ __forceinline__ void pv_one(f32x16& od, lds_cptr vp, bf16x8 pa0, bf16x8 pa1, bf16x8 pa2, bf16x8 pa3) {
;   const s16x4 l0 = vtr(vp + v_rd_off(D0, 0, 0)), h0 = vtr(vp + v_rd_off(D0, 0, 1)), l1 = vtr(vp + v_rd_off(D0, 1, 0)), h1 = vtr(vp + v_rd_off(D0, 1, 1));
;   const s16x4 l2 = vtr(vp + v_rd_off(D0, 2, 0)), h2 = vtr(vp + v_rd_off(D0, 2, 1)), l3 = vtr(vp + v_rd_off(D0, 3, 0)), h3 = vtr(vp + v_rd_off(D0, 3, 1));
;     ...
;   od = __builtin_amdgcn_mfma_f32_32x32x16_bf16(pa0, PK(l0, h0), od, 0, 0, 0);
;   od = __builtin_amdgcn_mfma_f32_32x32x16_bf16(pa1, PK(l1, h1), od, 0, 0, 0);
;   od = __builtin_amdgcn_mfma_f32_32x32x16_bf16(pa2, PK(l2, h2), od, 0, 0, 0);
;   od = __builtin_amdgcn_mfma_f32_32x32x16_bf16(pa3, PK(l3, h3), od, 0, 0, 0);
;     ...
; }
; __device__ __forceinline__ void pv_d0(f32x16* o, lds_cptr vp, bf16x8 pa0, bf16x8 pa1, bf16x8 pa2, bf16x8 pa3) {
;   pv_one<0>(o[0], vp, pa0, pa1, pa2, pa3); pv_one<1>(o[1], vp, pa0, pa1, pa2, pa3);
.Lf1_750:
	ds_read_b64_tr_b16 v[180:181], v203 offset:16384
	ds_read_b64_tr_b16 v[182:183], v203 offset:18432
	ds_read_b64_tr_b16 v[188:189], v203 offset:18944
	ds_read_b64_tr_b16 v[186:187], v203 offset:16896
	s_waitcnt lgkmcnt(2)
	v_mfma_f32_32x32x16_bf16 v[0:15], v[92:95], v[180:183], v[0:15]
	ds_read_b64_tr_b16 v[180:181], v203 offset:20480
	ds_read_b64_tr_b16 v[182:183], v203 offset:22528
	ds_read_b64_tr_b16 v[192:193], v203 offset:23040
	ds_read_b64_tr_b16 v[190:191], v203 offset:20992
	s_waitcnt lgkmcnt(2)
	v_mfma_f32_32x32x16_bf16 v[0:15], v[88:91], v[180:183], v[0:15]
	ds_read_b64_tr_b16 v[180:181], v203 offset:24576
	ds_read_b64_tr_b16 v[182:183], v203 offset:26624
	ds_read_b64_tr_b16 v[222:223], v203 offset:27136
	ds_read_b64_tr_b16 v[220:221], v203 offset:25088
	v_mfma_f32_32x32x16_bf16 v[16:31], v[92:95], v[186:189], v[16:31]
	s_waitcnt lgkmcnt(2)
	v_mfma_f32_32x32x16_bf16 v[0:15], v[84:87], v[180:183], v[0:15]
	ds_read_b64_tr_b16 v[180:181], v203 offset:28672
	ds_read_b64_tr_b16 v[182:183], v203 offset:30720
	ds_read_b64_tr_b16 v[226:227], v203 offset:31232
	ds_read_b64_tr_b16 v[224:225], v203 offset:29184
	v_mfma_f32_32x32x16_bf16 v[16:31], v[88:91], v[190:193], v[16:31]
	s_waitcnt lgkmcnt(2)
	v_mfma_f32_32x32x16_bf16 v[0:15], v[80:83], v[180:183], v[0:15]
	v_max_f32_e32 v180, v96, v97
	v_max3_f32 v180, v180, v98, v99
	v_max3_f32 v180, v180, v100, v101
	v_max3_f32 v92, v180, v102, v103
	v_max3_f32 v92, v92, v104, v105
	v_max3_f32 v92, v92, v106, v107
	v_max3_f32 v92, v92, v108, v109
	v_mfma_f32_32x32x16_bf16 v[16:31], v[84:87], v[220:223], v[16:31]
	v_max3_f32 v92, v92, v110, v111
	v_max3_f32 v92, v92, v64, v65
	v_max3_f32 v92, v92, v66, v67
	v_max3_f32 v88, v92, v68, v69
	v_max3_f32 v88, v88, v70, v71
	v_max3_f32 v88, v88, v72, v73
	v_max3_f32 v88, v88, v74, v75
	v_max3_f32 v88, v88, v76, v77
	s_waitcnt lgkmcnt(0)
	v_mfma_f32_32x32x16_bf16 v[16:31], v[80:83], v[224:227], v[16:31]
	v_max3_f32 v88, v88, v78, v79
	v_cmp_ge_f32_e32 vcc, s86, v88
	s_cmp_eq_u64 vcc, exec
	v_mov_b32_e32 v84, 1.0
	s_cbranch_scc0 .Lf1_758

; __device__ __forceinline__ s16x4 vtr(lds_cptr p) { return __builtin_bit_cast(s16x4, __builtin_amdgcn_ds_read_tr16_b64_v4i16((LAS v4i16_t*)p)); }
; template <bool FIRST> __device__ __forceinline__ void partialSM(f32x16& p0, f32x16& p1, float& mref, f32x16& negm, float& alpha) {
;   constexpr float THRL = THR * 1.4426950408889634f;
;   float pmax = p0[0];
; #pragma unroll
;   for (int r = 1; r < 16; ++r) pmax = fmaxf(pmax, p0[r]);
; #pragma unroll
;   for (int r = 0; r < 16; ++r) pmax = fmaxf(pmax, p1[r]);
;   { auto rr = __builtin_amdgcn_permlane32_swap(__float_as_uint(pmax), __float_as_uint(pmax), false, false);
;     pmax = fmaxf(__uint_as_float(rr[0]), __uint_as_float(rr[1])); }
;   if (!FIRST && __builtin_expect(__all(pmax <= THRL), 1)) { alpha = 1.f; }
; template <int D0> __device__ __forceinline__ void pv_one(f32x16& od, lds_cptr vp, bf16x8 pa0, bf16x8 pa1, bf16x8 pa2, bf16x8 pa3) {
;   const s16x4 l0 = vtr(vp + v_rd_off(D0, 0, 0)), h0 = vtr(vp + v_rd_off(D0, 0, 1)), l1 = vtr(vp + v_rd_off(D0, 1, 0)), h1 = vtr(vp + v_rd_off(D0, 1, 1));
;   const s16x4 l2 = vtr(vp + v_rd_off(D0, 2, 0)), h2 = vtr(vp + v_rd_off(D0, 2, 1)), l3 = vtr(vp + v_rd_off(D0, 3, 0)), h3 = vtr(vp + v_rd_off(D0, 3, 1));
;     ...
;   od = __builtin_amdgcn_mfma_f32_32x32x16_bf16(pa0, PK(l0, h0), od, 0, 0, 0);
;   od = __builtin_amdgcn_mfma_f32_32x32x16_bf16(pa1, PK(l1, h1), od, 0, 0, 0);
;   od = __builtin_amdgcn_mfma_f32_32x32x16_bf16(pa2, PK(l2, h2), od, 0, 0, 0);
;   od = __builtin_amdgcn_mfma_f32_32x32x16_bf16(pa3, PK(l3, h3), od, 0, 0, 0);
;     ...
; }
; __device__ __forceinline__ void pv_d0(f32x16* o, lds_cptr vp, bf16x8 pa0, bf16x8 pa1, bf16x8 pa2, bf16x8 pa3) {
;   pv_one<0>(o[0], vp, pa0, pa1, pa2, pa3); pv_one<1>(o[1], vp, pa0, pa1, pa2, pa3);
.Lf2_741:
	s_and_b32 s48, s89, 0xc000
	ds_read_b64_tr_b16 v[64:65], v203 offset:32768
	ds_read_b64_tr_b16 v[66:67], v203 offset:34816
	ds_read_b64_tr_b16 v[70:71], v203 offset:35328
	ds_read_b64_tr_b16 v[68:69], v203 offset:33280
	s_waitcnt lgkmcnt(2)
	v_mfma_f32_32x32x16_bf16 v[0:15], v[60:63], v[64:67], v[0:15]
	ds_read_b64_tr_b16 v[64:65], v203 offset:36864
	ds_read_b64_tr_b16 v[66:67], v203 offset:38912
	ds_read_b64_tr_b16 v[74:75], v203 offset:39424
	ds_read_b64_tr_b16 v[72:73], v203 offset:37376
	s_waitcnt lgkmcnt(2)
	v_mfma_f32_32x32x16_bf16 v[0:15], v[56:59], v[64:67], v[0:15]
	ds_read_b64_tr_b16 v[64:65], v203 offset:40960
	ds_read_b64_tr_b16 v[66:67], v203 offset:43008
	ds_read_b64_tr_b16 v[78:79], v203 offset:43520
	ds_read_b64_tr_b16 v[76:77], v203 offset:41472
	v_mfma_f32_32x32x16_bf16 v[16:31], v[60:63], v[68:71], v[16:31]
	s_waitcnt lgkmcnt(2)
	v_mfma_f32_32x32x16_bf16 v[0:15], v[52:55], v[64:67], v[0:15]
	ds_read_b64_tr_b16 v[64:65], v203 offset:45056
	ds_read_b64_tr_b16 v[66:67], v203 offset:47104
	ds_read_b64_tr_b16 v[186:187], v203 offset:47616
	ds_read_b64_tr_b16 v[184:185], v203 offset:45568
	v_mfma_f32_32x32x16_bf16 v[16:31], v[56:59], v[72:75], v[16:31]
	s_waitcnt lgkmcnt(2)
	v_mfma_f32_32x32x16_bf16 v[0:15], v[48:51], v[64:67], v[0:15]
	v_max_f32_e32 v64, v96, v97
	v_max3_f32 v64, v64, v98, v99
	v_max3_f32 v60, v64, v100, v101
	v_max3_f32 v60, v60, v102, v103
	v_max3_f32 v60, v60, v104, v105
	v_max3_f32 v60, v60, v106, v107
	v_max3_f32 v60, v60, v108, v109
	v_mfma_f32_32x32x16_bf16 v[16:31], v[52:55], v[76:79], v[16:31]
	v_max3_f32 v60, v60, v110, v111
	v_max3_f32 v60, v60, v80, v81
	v_max3_f32 v56, v60, v82, v83
	v_max3_f32 v56, v56, v84, v85
	v_max3_f32 v56, v56, v86, v87
	v_max3_f32 v56, v56, v88, v89
	v_max3_f32 v56, v56, v90, v91
	v_max3_f32 v56, v56, v92, v93
	s_waitcnt lgkmcnt(0)
	v_mfma_f32_32x32x16_bf16 v[16:31], v[48:51], v[184:187], v[16:31]
	v_max3_f32 v56, v56, v94, v95
	v_cmp_ge_f32_e32 vcc, s86, v56
	s_cmp_eq_u64 vcc, exec
	s_cbranch_scc0 .Lf2_757
	v_mov_b32_e32 v169, 1.0

; __device__ __forceinline__ s16x4 vtr(lds_cptr p) { return __builtin_bit_cast(s16x4, __builtin_amdgcn_ds_read_tr16_b64_v4i16((LAS v4i16_t*)p)); }
; template <bool FIRST> __device__ __forceinline__ void partialSM(f32x16& p0, f32x16& p1, float& mref, f32x16& negm, float& alpha) {
;   constexpr float THRL = THR * 1.4426950408889634f;
;   float pmax = p0[0];
; #pragma unroll
;   for (int r = 1; r < 16; ++r) pmax = fmaxf(pmax, p0[r]);
; #pragma unroll
;   for (int r = 0; r < 16; ++r) pmax = fmaxf(pmax, p1[r]);
;   { auto rr = __builtin_amdgcn_permlane32_swap(__float_as_uint(pmax), __float_as_uint(pmax), false, false);
;     pmax = fmaxf(__uint_as_float(rr[0]), __uint_as_float(rr[1])); }
;   if (!FIRST && __builtin_expect(__all(pmax <= THRL), 1)) { alpha = 1.f; }
; template <int D0> __device__ __forceinline__ void pv_one(f32x16& od, lds_cptr vp, bf16x8 pa0, bf16x8 pa1, bf16x8 pa2, bf16x8 pa3) {
;   const s16x4 l0 = vtr(vp + v_rd_off(D0, 0, 0)), h0 = vtr(vp + v_rd_off(D0, 0, 1)), l1 = vtr(vp + v_rd_off(D0, 1, 0)), h1 = vtr(vp + v_rd_off(D0, 1, 1));
;   const s16x4 l2 = vtr(vp + v_rd_off(D0, 2, 0)), h2 = vtr(vp + v_rd_off(D0, 2, 1)), l3 = vtr(vp + v_rd_off(D0, 3, 0)), h3 = vtr(vp + v_rd_off(D0, 3, 1));
;     ...
;   od = __builtin_amdgcn_mfma_f32_32x32x16_bf16(pa0, PK(l0, h0), od, 0, 0, 0);
;   od = __builtin_amdgcn_mfma_f32_32x32x16_bf16(pa1, PK(l1, h1), od, 0, 0, 0);
;   od = __builtin_amdgcn_mfma_f32_32x32x16_bf16(pa2, PK(l2, h2), od, 0, 0, 0);
;   od = __builtin_amdgcn_mfma_f32_32x32x16_bf16(pa3, PK(l3, h3), od, 0, 0, 0);
;     ...
; }
; __device__ __forceinline__ void pv_d0(f32x16* o, lds_cptr vp, bf16x8 pa0, bf16x8 pa1, bf16x8 pa2, bf16x8 pa3) {
;   pv_one<0>(o[0], vp, pa0, pa1, pa2, pa3); pv_one<1>(o[1], vp, pa0, pa1, pa2, pa3);
.Lf2_750:
	ds_read_b64_tr_b16 v[180:181], v203 offset:49152
	ds_read_b64_tr_b16 v[182:183], v203 offset:51200
	ds_read_b64_tr_b16 v[188:189], v203 offset:51712
	ds_read_b64_tr_b16 v[186:187], v203 offset:49664
	s_waitcnt lgkmcnt(2)
	v_mfma_f32_32x32x16_bf16 v[0:15], v[92:95], v[180:183], v[0:15]
	ds_read_b64_tr_b16 v[180:181], v203 offset:53248
	ds_read_b64_tr_b16 v[182:183], v203 offset:55296
	ds_read_b64_tr_b16 v[192:193], v203 offset:55808
	ds_read_b64_tr_b16 v[190:191], v203 offset:53760
	s_waitcnt lgkmcnt(2)
	v_mfma_f32_32x32x16_bf16 v[0:15], v[88:91], v[180:183], v[0:15]
	ds_read_b64_tr_b16 v[180:181], v203 offset:57344
	ds_read_b64_tr_b16 v[182:183], v203 offset:59392
	ds_read_b64_tr_b16 v[222:223], v203 offset:59904
	ds_read_b64_tr_b16 v[220:221], v203 offset:57856
	v_mfma_f32_32x32x16_bf16 v[16:31], v[92:95], v[186:189], v[16:31]
	s_waitcnt lgkmcnt(2)
	v_mfma_f32_32x32x16_bf16 v[0:15], v[84:87], v[180:183], v[0:15]
	ds_read_b64_tr_b16 v[180:181], v203 offset:61440
	ds_read_b64_tr_b16 v[182:183], v203 offset:63488
	ds_read_b64_tr_b16 v[226:227], v203 offset:64000
	ds_read_b64_tr_b16 v[224:225], v203 offset:61952
	v_mfma_f32_32x32x16_bf16 v[16:31], v[88:91], v[190:193], v[16:31]
	s_waitcnt lgkmcnt(2)
	v_mfma_f32_32x32x16_bf16 v[0:15], v[80:83], v[180:183], v[0:15]
	v_max_f32_e32 v180, v96, v97
	v_max3_f32 v180, v180, v98, v99
	v_max3_f32 v180, v180, v100, v101
	v_max3_f32 v92, v180, v102, v103
	v_max3_f32 v92, v92, v104, v105
	v_max3_f32 v92, v92, v106, v107
	v_max3_f32 v92, v92, v108, v109
	v_mfma_f32_32x32x16_bf16 v[16:31], v[84:87], v[220:223], v[16:31]
	v_max3_f32 v92, v92, v110, v111
	v_max3_f32 v92, v92, v64, v65
	v_max3_f32 v92, v92, v66, v67
	v_max3_f32 v88, v92, v68, v69
	v_max3_f32 v88, v88, v70, v71
	v_max3_f32 v88, v88, v72, v73
	v_max3_f32 v88, v88, v74, v75
	v_max3_f32 v88, v88, v76, v77
	s_waitcnt lgkmcnt(0)
	v_mfma_f32_32x32x16_bf16 v[16:31], v[80:83], v[224:227], v[16:31]
	v_max3_f32 v88, v88, v78, v79
	v_cmp_ge_f32_e32 vcc, s86, v88
	s_cmp_eq_u64 vcc, exec
	v_mov_b32_e32 v84, 1.0
	s_cbranch_scc0 .Lf2_758

; __device__ __forceinline__ s16x4 vtr(lds_cptr p) { return __builtin_bit_cast(s16x4, __builtin_amdgcn_ds_read_tr16_b64_v4i16((LAS v4i16_t*)p)); }
; template <bool FIRST> __device__ __forceinline__ void partialSM(f32x16& p0, f32x16& p1, float& mref, f32x16& negm, float& alpha) {
;   constexpr float THRL = THR * 1.4426950408889634f;
;   float pmax = p0[0];
; #pragma unroll
;   for (int r = 1; r < 16; ++r) pmax = fmaxf(pmax, p0[r]);
; #pragma unroll
;   for (int r = 0; r < 16; ++r) pmax = fmaxf(pmax, p1[r]);
;   { auto rr = __builtin_amdgcn_permlane32_swap(__float_as_uint(pmax), __float_as_uint(pmax), false, false);
;     pmax = fmaxf(__uint_as_float(rr[0]), __uint_as_float(rr[1])); }
;   if (!FIRST && __builtin_expect(__all(pmax <= THRL), 1)) { alpha = 1.f; }
; template <int D0> __device__ __forceinline__ void pv_one(f32x16& od, lds_cptr vp, bf16x8 pa0, bf16x8 pa1, bf16x8 pa2, bf16x8 pa3) {
;   const s16x4 l0 = vtr(vp + v_rd_off(D0, 0, 0)), h0 = vtr(vp + v_rd_off(D0, 0, 1)), l1 = vtr(vp + v_rd_off(D0, 1, 0)), h1 = vtr(vp + v_rd_off(D0, 1, 1));
;   const s16x4 l2 = vtr(vp + v_rd_off(D0, 2, 0)), h2 = vtr(vp + v_rd_off(D0, 2, 1)), l3 = vtr(vp + v_rd_off(D0, 3, 0)), h3 = vtr(vp + v_rd_off(D0, 3, 1));
;     ...
;   od = __builtin_amdgcn_mfma_f32_32x32x16_bf16(pa0, PK(l0, h0), od, 0, 0, 0);
;   od = __builtin_amdgcn_mfma_f32_32x32x16_bf16(pa1, PK(l1, h1), od, 0, 0, 0);
;   od = __builtin_amdgcn_mfma_f32_32x32x16_bf16(pa2, PK(l2, h2), od, 0, 0, 0);
;   od = __builtin_amdgcn_mfma_f32_32x32x16_bf16(pa3, PK(l3, h3), od, 0, 0, 0);
;     ...
; }
; __device__ __forceinline__ void pv_d0(f32x16* o, lds_cptr vp, bf16x8 pa0, bf16x8 pa1, bf16x8 pa2, bf16x8 pa3) {
;   pv_one<0>(o[0], vp, pa0, pa1, pa2, pa3); pv_one<1>(o[1], vp, pa0, pa1, pa2, pa3);
.LBB0_741:
	s_and_b32 s48, s89, 0xc000
	v_add_u32_e32 v169, s48, v203
	ds_read_b64_tr_b16 v[64:65], v169
	ds_read_b64_tr_b16 v[66:67], v169 offset:2048
	ds_read_b64_tr_b16 v[70:71], v169 offset:2560
	ds_read_b64_tr_b16 v[68:69], v169 offset:512
	s_waitcnt lgkmcnt(2)
	v_mfma_f32_32x32x16_bf16 v[0:15], v[60:63], v[64:67], v[0:15]
	ds_read_b64_tr_b16 v[64:65], v169 offset:4096
	ds_read_b64_tr_b16 v[66:67], v169 offset:6144
	ds_read_b64_tr_b16 v[74:75], v169 offset:6656
	ds_read_b64_tr_b16 v[72:73], v169 offset:4608
	s_waitcnt lgkmcnt(2)
	v_mfma_f32_32x32x16_bf16 v[0:15], v[56:59], v[64:67], v[0:15]
	ds_read_b64_tr_b16 v[64:65], v169 offset:8192
	ds_read_b64_tr_b16 v[66:67], v169 offset:10240
	ds_read_b64_tr_b16 v[78:79], v169 offset:10752
	ds_read_b64_tr_b16 v[76:77], v169 offset:8704
	v_mfma_f32_32x32x16_bf16 v[16:31], v[60:63], v[68:71], v[16:31]
	s_waitcnt lgkmcnt(2)
	v_mfma_f32_32x32x16_bf16 v[0:15], v[52:55], v[64:67], v[0:15]
	ds_read_b64_tr_b16 v[64:65], v169 offset:12288
	ds_read_b64_tr_b16 v[66:67], v169 offset:14336
	ds_read_b64_tr_b16 v[186:187], v169 offset:14848
	ds_read_b64_tr_b16 v[184:185], v169 offset:12800
	v_mfma_f32_32x32x16_bf16 v[16:31], v[56:59], v[72:75], v[16:31]
	s_waitcnt lgkmcnt(2)
	v_mfma_f32_32x32x16_bf16 v[0:15], v[48:51], v[64:67], v[0:15]
	v_max_f32_e32 v64, v96, v97
	v_max3_f32 v64, v64, v98, v99
	v_max3_f32 v60, v64, v100, v101
	v_max3_f32 v60, v60, v102, v103
	v_max3_f32 v60, v60, v104, v105
	v_max3_f32 v60, v60, v106, v107
	v_max3_f32 v60, v60, v108, v109
	v_mfma_f32_32x32x16_bf16 v[16:31], v[52:55], v[76:79], v[16:31]
	v_max3_f32 v60, v60, v110, v111
	v_max3_f32 v60, v60, v80, v81
	v_max3_f32 v56, v60, v82, v83
	v_max3_f32 v56, v56, v84, v85
	v_max3_f32 v56, v56, v86, v87
	v_max3_f32 v56, v56, v88, v89
	v_max3_f32 v56, v56, v90, v91
	v_max3_f32 v56, v56, v92, v93
	s_waitcnt lgkmcnt(0)
	v_mfma_f32_32x32x16_bf16 v[16:31], v[48:51], v[184:187], v[16:31]
	v_max3_f32 v56, v56, v94, v95
	v_cmp_ge_f32_e32 vcc, s86, v56
	s_cmp_eq_u64 vcc, exec
	s_cbranch_scc0 .LBB0_757
	v_mov_b32_e32 v169, 1.0

; __device__ __forceinline__ s16x4 vtr(lds_cptr p) { return __builtin_bit_cast(s16x4, __builtin_amdgcn_ds_read_tr16_b64_v4i16((LAS v4i16_t*)p)); }
; template <bool FIRST> __device__ __forceinline__ void partialSM(f32x16& p0, f32x16& p1, float& mref, f32x16& negm, float& alpha) {
;   constexpr float THRL = THR * 1.4426950408889634f;
;   float pmax = p0[0];
; #pragma unroll
;   for (int r = 1; r < 16; ++r) pmax = fmaxf(pmax, p0[r]);
; #pragma unroll
;   for (int r = 0; r < 16; ++r) pmax = fmaxf(pmax, p1[r]);
;   { auto rr = __builtin_amdgcn_permlane32_swap(__float_as_uint(pmax), __float_as_uint(pmax), false, false);
;     pmax = fmaxf(__uint_as_float(rr[0]), __uint_as_float(rr[1])); }
;   if (!FIRST && __builtin_expect(__all(pmax <= THRL), 1)) { alpha = 1.f; }
; template <int D0> __device__ __forceinline__ void pv_one(f32x16& od, lds_cptr vp, bf16x8 pa0, bf16x8 pa1, bf16x8 pa2, bf16x8 pa3) {
;   const s16x4 l0 = vtr(vp + v_rd_off(D0, 0, 0)), h0 = vtr(vp + v_rd_off(D0, 0, 1)), l1 = vtr(vp + v_rd_off(D0, 1, 0)), h1 = vtr(vp + v_rd_off(D0, 1, 1));
;   const s16x4 l2 = vtr(vp + v_rd_off(D0, 2, 0)), h2 = vtr(vp + v_rd_off(D0, 2, 1)), l3 = vtr(vp + v_rd_off(D0, 3, 0)), h3 = vtr(vp + v_rd_off(D0, 3, 1));
;     ...
;   od = __builtin_amdgcn_mfma_f32_32x32x16_bf16(pa0, PK(l0, h0), od, 0, 0, 0);
;   od = __builtin_amdgcn_mfma_f32_32x32x16_bf16(pa1, PK(l1, h1), od, 0, 0, 0);
;   od = __builtin_amdgcn_mfma_f32_32x32x16_bf16(pa2, PK(l2, h2), od, 0, 0, 0);
;   od = __builtin_amdgcn_mfma_f32_32x32x16_bf16(pa3, PK(l3, h3), od, 0, 0, 0);
;     ...
; }
; __device__ __forceinline__ void pv_d0(f32x16* o, lds_cptr vp, bf16x8 pa0, bf16x8 pa1, bf16x8 pa2, bf16x8 pa3) {
;   pv_one<0>(o[0], vp, pa0, pa1, pa2, pa3); pv_one<1>(o[1], vp, pa0, pa1, pa2, pa3);
.LBB0_750:
	v_add_u32_e32 v185, s41, v203
	ds_read_b64_tr_b16 v[180:181], v185
	ds_read_b64_tr_b16 v[182:183], v185 offset:2048
	ds_read_b64_tr_b16 v[188:189], v185 offset:2560
	ds_read_b64_tr_b16 v[186:187], v185 offset:512
	s_waitcnt lgkmcnt(2)
	v_mfma_f32_32x32x16_bf16 v[0:15], v[92:95], v[180:183], v[0:15]
	ds_read_b64_tr_b16 v[180:181], v185 offset:4096
	ds_read_b64_tr_b16 v[182:183], v185 offset:6144
	ds_read_b64_tr_b16 v[192:193], v185 offset:6656
	ds_read_b64_tr_b16 v[190:191], v185 offset:4608
	s_waitcnt lgkmcnt(2)
	v_mfma_f32_32x32x16_bf16 v[0:15], v[88:91], v[180:183], v[0:15]
	ds_read_b64_tr_b16 v[180:181], v185 offset:8192
	ds_read_b64_tr_b16 v[182:183], v185 offset:10240
	ds_read_b64_tr_b16 v[222:223], v185 offset:10752
	ds_read_b64_tr_b16 v[220:221], v185 offset:8704
	v_mfma_f32_32x32x16_bf16 v[16:31], v[92:95], v[186:189], v[16:31]
	s_waitcnt lgkmcnt(2)
	v_mfma_f32_32x32x16_bf16 v[0:15], v[84:87], v[180:183], v[0:15]
	ds_read_b64_tr_b16 v[180:181], v185 offset:12288
	ds_read_b64_tr_b16 v[182:183], v185 offset:14336
	ds_read_b64_tr_b16 v[226:227], v185 offset:14848
	ds_read_b64_tr_b16 v[224:225], v185 offset:12800
	v_mfma_f32_32x32x16_bf16 v[16:31], v[88:91], v[190:193], v[16:31]
	s_waitcnt lgkmcnt(2)
	v_mfma_f32_32x32x16_bf16 v[0:15], v[80:83], v[180:183], v[0:15]
	v_max_f32_e32 v180, v96, v97
	v_max3_f32 v180, v180, v98, v99
	v_max3_f32 v180, v180, v100, v101
	v_max3_f32 v92, v180, v102, v103
	v_max3_f32 v92, v92, v104, v105
	v_max3_f32 v92, v92, v106, v107
	v_max3_f32 v92, v92, v108, v109
	v_mfma_f32_32x32x16_bf16 v[16:31], v[84:87], v[220:223], v[16:31]
	v_max3_f32 v92, v92, v110, v111
	v_max3_f32 v92, v92, v64, v65
	v_max3_f32 v92, v92, v66, v67
	v_max3_f32 v88, v92, v68, v69
	v_max3_f32 v88, v88, v70, v71
	v_max3_f32 v88, v88, v72, v73
	v_max3_f32 v88, v88, v74, v75
	v_max3_f32 v88, v88, v76, v77
	s_waitcnt lgkmcnt(0)
	v_mfma_f32_32x32x16_bf16 v[16:31], v[80:83], v[224:227], v[16:31]
	v_max3_f32 v88, v88, v78, v79
	v_cmp_ge_f32_e32 vcc, s86, v88
	s_cmp_eq_u64 vcc, exec
	v_mov_b32_e32 v84, 1.0
	s_cbranch_scc0 .LBB0_758

; template <bool FIRST> __device__ __forceinline__ void partialSM(f32x16& p0, f32x16& p1, float& mref, f32x16& negm, float& alpha) {
;     ...
;   { auto rr = __builtin_amdgcn_permlane32_swap(__float_as_uint(pmax), __float_as_uint(pmax), false, false);
;     pmax = fmaxf(__uint_as_float(rr[0]), __uint_as_float(rr[1])); }
;   if (!FIRST && __builtin_expect(__all(pmax <= THRL), 1)) { alpha = 1.f; }
;   else { const float dl = FIRST ? pmax : fmaxf(pmax, 0.f); mref += dl; alpha = FIRST ? 1.f : __builtin_amdgcn_exp2f(-dl);
; #pragma unroll
;     for (int r = 0; r < 16; ++r) { p0[r] -= dl; p1[r] -= dl; }
;     const float nm = -mref;
; #pragma unroll
;     for (int r = 0; r < 16; ++r) negm[r] = nm; }
.LBB0_757:
	v_mov_b32_e32 v52, v56
	s_nop 1
	v_permlane32_swap_b32_e32 v56, v52
	v_max_f32_e32 v52, v56, v52
	v_max_f32_e32 v32, v52, v52
	v_max_f32_e32 v32, 0, v32
	v_exp_f32_e64 v169, -v32
	v_add_f32_e32 v161, v161, v32
	v_xor_b32_e32 v48, 0x80000000, v161
	v_pk_add_f32 v[96:97], v[96:97], v[32:33] op_sel_hi:[1,0] neg_lo:[0,1] neg_hi:[0,1]
	v_pk_add_f32 v[98:99], v[98:99], v[32:33] op_sel_hi:[1,0] neg_lo:[0,1] neg_hi:[0,1]
	v_pk_add_f32 v[100:101], v[100:101], v[32:33] op_sel_hi:[1,0] neg_lo:[0,1] neg_hi:[0,1]
	v_pk_add_f32 v[102:103], v[102:103], v[32:33] op_sel_hi:[1,0] neg_lo:[0,1] neg_hi:[0,1]
	v_pk_add_f32 v[104:105], v[104:105], v[32:33] op_sel_hi:[1,0] neg_lo:[0,1] neg_hi:[0,1]
	v_pk_add_f32 v[106:107], v[106:107], v[32:33] op_sel_hi:[1,0] neg_lo:[0,1] neg_hi:[0,1]
	v_pk_add_f32 v[108:109], v[108:109], v[32:33] op_sel_hi:[1,0] neg_lo:[0,1] neg_hi:[0,1]
	v_pk_add_f32 v[110:111], v[110:111], v[32:33] op_sel_hi:[1,0] neg_lo:[0,1] neg_hi:[0,1]
	v_sub_f32_e32 v95, v95, v32
	v_sub_f32_e32 v94, v94, v32
	v_sub_f32_e32 v93, v93, v32
	v_sub_f32_e32 v92, v92, v32
	v_sub_f32_e32 v91, v91, v32
	v_sub_f32_e32 v90, v90, v32
	v_sub_f32_e32 v89, v89, v32
	v_sub_f32_e32 v88, v88, v32
	v_sub_f32_e32 v87, v87, v32
	v_sub_f32_e32 v86, v86, v32
	v_sub_f32_e32 v85, v85, v32
	v_sub_f32_e32 v84, v84, v32
	v_sub_f32_e32 v83, v83, v32
	v_sub_f32_e32 v82, v82, v32
	v_sub_f32_e32 v81, v81, v32
	v_sub_f32_e32 v80, v80, v32
	v_mov_b32_e32 v49, v48
	v_mov_b32_e32 v50, v48
	v_mov_b32_e32 v51, v48
	v_mov_b32_e32 v52, v48
	v_mov_b32_e32 v53, v48
	v_mov_b32_e32 v54, v48
	v_mov_b32_e32 v55, v48
	v_mov_b32_e32 v56, v48
	v_mov_b32_e32 v57, v48
	v_mov_b32_e32 v58, v48
	v_mov_b32_e32 v59, v48
	v_mov_b32_e32 v60, v48
	v_mov_b32_e32 v61, v48
	v_mov_b32_e32 v62, v48
	v_mov_b32_e32 v63, v48
	v_mov_b32_e32 v32, v48
	v_mov_b32_e32 v33, v48
	v_mov_b32_e32 v34, v48
	v_mov_b32_e32 v35, v48
	v_mov_b32_e32 v36, v48
	v_mov_b32_e32 v37, v48
	v_mov_b32_e32 v38, v48
	v_mov_b32_e32 v39, v48
	v_mov_b32_e32 v40, v48
	v_mov_b32_e32 v41, v48
	v_mov_b32_e32 v42, v48
	v_mov_b32_e32 v43, v48
	v_mov_b32_e32 v44, v48
	v_mov_b32_e32 v45, v48
	v_mov_b32_e32 v46, v48
	v_mov_b32_e32 v47, v48
	v_cmp_gt_f32_e32 vcc, 1.0, v169
	s_cbranch_vccnz .LBB0_743
	s_branch .LBB0_746
.LBB0_758:
	v_mov_b32_e32 v89, v88
	s_nop 1
	v_permlane32_swap_b32_e32 v88, v89
	v_max_f32_e32 v85, v88, v89
	v_max_f32_e32 v32, v85, v85
	v_max_f32_e32 v32, 0, v32
	v_exp_f32_e64 v84, -v32
	v_add_f32_e32 v161, v161, v32
	v_xor_b32_e32 v48, 0x80000000, v161
	v_pk_add_f32 v[96:97], v[96:97], v[32:33] op_sel_hi:[1,0] neg_lo:[0,1] neg_hi:[0,1]
	v_pk_add_f32 v[98:99], v[98:99], v[32:33] op_sel_hi:[1,0] neg_lo:[0,1] neg_hi:[0,1]
	v_pk_add_f32 v[100:101], v[100:101], v[32:33] op_sel_hi:[1,0] neg_lo:[0,1] neg_hi:[0,1]
	v_pk_add_f32 v[102:103], v[102:103], v[32:33] op_sel_hi:[1,0] neg_lo:[0,1] neg_hi:[0,1]
	v_pk_add_f32 v[104:105], v[104:105], v[32:33] op_sel_hi:[1,0] neg_lo:[0,1] neg_hi:[0,1]
	v_pk_add_f32 v[106:107], v[106:107], v[32:33] op_sel_hi:[1,0] neg_lo:[0,1] neg_hi:[0,1]
	v_pk_add_f32 v[108:109], v[108:109], v[32:33] op_sel_hi:[1,0] neg_lo:[0,1] neg_hi:[0,1]
	v_pk_add_f32 v[110:111], v[110:111], v[32:33] op_sel_hi:[1,0] neg_lo:[0,1] neg_hi:[0,1]
	v_sub_f32_e32 v79, v79, v32
	v_sub_f32_e32 v78, v78, v32
	v_sub_f32_e32 v77, v77, v32
	v_sub_f32_e32 v76, v76, v32
	v_sub_f32_e32 v75, v75, v32
	v_sub_f32_e32 v74, v74, v32
	v_sub_f32_e32 v73, v73, v32
	v_sub_f32_e32 v72, v72, v32
	v_sub_f32_e32 v71, v71, v32
	v_sub_f32_e32 v70, v70, v32
	v_sub_f32_e32 v69, v69, v32
	v_sub_f32_e32 v68, v68, v32
	v_sub_f32_e32 v67, v67, v32
	v_sub_f32_e32 v66, v66, v32
	v_sub_f32_e32 v65, v65, v32
	v_sub_f32_e32 v64, v64, v32
	v_mov_b32_e32 v49, v48
	v_mov_b32_e32 v50, v48
	v_mov_b32_e32 v51, v48
	v_mov_b32_e32 v52, v48
	v_mov_b32_e32 v53, v48
	v_mov_b32_e32 v54, v48
	v_mov_b32_e32 v55, v48
	v_mov_b32_e32 v56, v48
	v_mov_b32_e32 v57, v48
	v_mov_b32_e32 v58, v48
	v_mov_b32_e32 v59, v48
	v_mov_b32_e32 v60, v48
	v_mov_b32_e32 v61, v48
	v_mov_b32_e32 v62, v48
	v_mov_b32_e32 v63, v48
	v_mov_b32_e32 v32, v48
	v_mov_b32_e32 v33, v48
	v_mov_b32_e32 v34, v48
	v_mov_b32_e32 v35, v48
	v_mov_b32_e32 v36, v48
	v_mov_b32_e32 v37, v48
	v_mov_b32_e32 v38, v48
	v_mov_b32_e32 v39, v48
	v_mov_b32_e32 v40, v48
	v_mov_b32_e32 v41, v48
	v_mov_b32_e32 v42, v48
	v_mov_b32_e32 v43, v48
	v_mov_b32_e32 v44, v48
	v_mov_b32_e32 v45, v48
	v_mov_b32_e32 v46, v48
	v_mov_b32_e32 v47, v48
	v_cmp_gt_f32_e32 vcc, 1.0, v84
	s_cbranch_vccnz .LBB0_752
	s_branch .LBB0_755
